# side_gemm1: split-K over all 8 waves (one K eighth each for both row tiles) so the dt weight rows are fetched once per workgroup; 48 instead of 80 strided loads per wave
# speedup vs baseline: 1.0046x; 1.0046x over previous
; #define GAS __attribute__((address_space(1)))
; __device__ __forceinline__ f32x4 mfma16(const bf16x8& a, const bf16x8& b, const f32x4& c) { return __builtin_amdgcn_mfma_f32_16x16x32_bf16(a, b, c, 0, 0, 0); }
; template <class F> __device__ __forceinline__ void skinny_tile(const GAS bf16* A, int lda, const GAS bf16* Bt, int K, int n0, int lane, F&& epi) {
;     const int fr = lane & 15, fq = lane >> 4;
;     const GAS bf16* ap = A + (size_t)fr * lda + fq * 8; const GAS bf16* bp = Bt + (size_t)(n0 + fr) * K + fq * 8;
;     f32x4 acc0 = {0.f, 0.f, 0.f, 0.f}, acc1 = {0.f, 0.f, 0.f, 0.f};
;     bf16x8 a[4], bb[4], a2[4], b2[4];
; #pragma unroll
;     for (int i = 0; i < 4; ++i) { a[i] = *(const GAS bf16x8*)(ap + i * 32); bb[i] = *(const GAS bf16x8*)(bp + i * 32); }
;     for (int k = 0; k < K; k += 256) {
; #pragma unroll
;         for (int i = 0; i < 4; ++i) { a2[i] = *(const GAS bf16x8*)(ap + k + 128 + i * 32); b2[i] = *(const GAS bf16x8*)(bp + k + 128 + i * 32); }
; #pragma unroll
;         for (int i = 0; i < 4; i += 2) { acc0 = mfma16(a[i], bb[i], acc0); acc1 = mfma16(a[i + 1], bb[i + 1], acc1); }
;         if (k + 256 < K) {
; #pragma unroll
;             for (int i = 0; i < 4; ++i) { a[i] = *(const GAS bf16x8*)(ap + k + 256 + i * 32); bb[i] = *(const GAS bf16x8*)(bp + k + 256 + i * 32); } }
; #pragma unroll
;         for (int i = 0; i < 4; i += 2) { acc0 = mfma16(a2[i], b2[i], acc0); acc1 = mfma16(a2[i + 1], b2[i + 1], acc1); } }
; __device__ __forceinline__ void side_gemm1(const Params& P, int seg) {
;     ...
;     for (int it = gw; it < nrt * 4; it += NGW) { const int rt = it >> 2, r0 = (rt < RS / 16) ? rt * 16 : RS + 48;
;         skinny_tile(xb + (size_t)r0 * DM, DM, Wt + (size_t)NPROJ * DM, DM, (it & 3) * 16, lane, [&](int row, int j, int col, float v) {
.Lsg1_new:
	s_mov_b32 s100, 0
	v_lshrrev_b32_e32 v116, 6, v172
	v_and_b32_e32 v117, 3, v116
	v_lshlrev_b32_e32 v18, 9, v116
	v_mov_b32_e32 v19, 0
	v_lshl_add_u64 v[232:233], v[4:5], 0, v[18:19]
	v_cmp_gt_u32_e64 s[54:55], 4, v116
	v_mov_b32_e32 v222, 0x10000
	v_mov_b32_e32 v220, 0xffff0000
	s_nop 1
	v_cndmask_b32_e64 v220, v220, v222, s[54:55]
	v_ashrrev_i32_e32 v221, 31, v220
	v_lshl_add_u64 v[234:235], v[232:233], 0, v[220:221]
	v_and_b32_e32 v236, 48, v172
	v_lshl_add_u32 v236, v28, 12, v236
	v_add_u32_e32 v236, v236, v18
	s_add_u32 s46, s40, 0x5000000
	s_addc_u32 s47, s41, 0
	s_add_u32 s48, s46, 0x10000
	s_addc_u32 s49, s47, 0
	s_add_u32 s50, s46, 0x20000
	s_addc_u32 s51, s47, 0
	s_add_u32 s52, s46, 0x30000
	s_addc_u32 s53, s47, 0
	global_load_dwordx4 v[68:71], v[232:233], off
	global_load_dwordx4 v[76:79], v[234:235], off
	global_load_dwordx4 v[72:75], v[232:233], off offset:64
	global_load_dwordx4 v[80:83], v[234:235], off offset:64
	global_load_dwordx4 v[84:87], v236, s[46:47]
	global_load_dwordx4 v[88:91], v236, s[46:47] offset:64
	global_load_dwordx4 v[92:95], v236, s[48:49]
	global_load_dwordx4 v[96:99], v236, s[48:49] offset:64
	global_load_dwordx4 v[100:103], v236, s[50:51]
	global_load_dwordx4 v[104:107], v236, s[50:51] offset:64
	global_load_dwordx4 v[108:111], v236, s[52:53]
	global_load_dwordx4 v[112:115], v236, s[52:53] offset:64
	global_load_dwordx4 v[120:123], v[232:233], off offset:128
	global_load_dwordx4 v[128:131], v[234:235], off offset:128
	global_load_dwordx4 v[124:127], v[232:233], off offset:192
	global_load_dwordx4 v[132:135], v[234:235], off offset:192
	global_load_dwordx4 v[136:139], v236, s[46:47] offset:128
	global_load_dwordx4 v[140:143], v236, s[46:47] offset:192
	global_load_dwordx4 v[144:147], v236, s[48:49] offset:128
	global_load_dwordx4 v[148:151], v236, s[48:49] offset:192
	global_load_dwordx4 v[152:155], v236, s[50:51] offset:128
	global_load_dwordx4 v[156:159], v236, s[50:51] offset:192
	global_load_dwordx4 v[160:163], v236, s[52:53] offset:128
	global_load_dwordx4 v[164:167], v236, s[52:53] offset:192
	global_load_dwordx4 v[184:187], v[232:233], off offset:256
	global_load_dwordx4 v[192:195], v[234:235], off offset:256
	global_load_dwordx4 v[188:191], v[232:233], off offset:320
	global_load_dwordx4 v[196:199], v[234:235], off offset:320
	global_load_dwordx4 v[200:203], v236, s[46:47] offset:256
	global_load_dwordx4 v[204:207], v236, s[46:47] offset:320
	global_load_dwordx4 v[208:211], v236, s[48:49] offset:256
	global_load_dwordx4 v[212:215], v236, s[48:49] offset:320
	global_load_dwordx4 v[216:219], v236, s[50:51] offset:256
	global_load_dwordx4 v[220:223], v236, s[50:51] offset:320
	global_load_dwordx4 v[224:227], v236, s[52:53] offset:256
	global_load_dwordx4 v[228:231], v236, s[52:53] offset:320
	s_waitcnt vmcnt(24)
	v_mfma_f32_16x16x32_bf16 v[36:39], v[68:71], v[84:87], 0
	v_mfma_f32_16x16x32_bf16 v[40:43], v[68:71], v[92:95], 0
	v_mfma_f32_16x16x32_bf16 v[44:47], v[68:71], v[100:103], 0
	v_mfma_f32_16x16x32_bf16 v[48:51], v[68:71], v[108:111], 0
	v_mfma_f32_16x16x32_bf16 v[52:55], v[76:79], v[84:87], 0
	v_mfma_f32_16x16x32_bf16 v[56:59], v[76:79], v[92:95], 0
	v_mfma_f32_16x16x32_bf16 v[60:63], v[76:79], v[100:103], 0
	v_mfma_f32_16x16x32_bf16 v[64:67], v[76:79], v[108:111], 0
	v_mfma_f32_16x16x32_bf16 v[36:39], v[72:75], v[88:91], v[36:39]
	v_mfma_f32_16x16x32_bf16 v[40:43], v[72:75], v[96:99], v[40:43]
	v_mfma_f32_16x16x32_bf16 v[44:47], v[72:75], v[104:107], v[44:47]
	v_mfma_f32_16x16x32_bf16 v[48:51], v[72:75], v[112:115], v[48:51]
	v_mfma_f32_16x16x32_bf16 v[52:55], v[80:83], v[88:91], v[52:55]
	v_mfma_f32_16x16x32_bf16 v[56:59], v[80:83], v[96:99], v[56:59]
	v_mfma_f32_16x16x32_bf16 v[60:63], v[80:83], v[104:107], v[60:63]
	v_mfma_f32_16x16x32_bf16 v[64:67], v[80:83], v[112:115], v[64:67]
	global_load_dwordx4 v[68:71], v[232:233], off offset:384
	global_load_dwordx4 v[76:79], v[234:235], off offset:384
	global_load_dwordx4 v[72:75], v[232:233], off offset:448
	global_load_dwordx4 v[80:83], v[234:235], off offset:448
	global_load_dwordx4 v[84:87], v236, s[46:47] offset:384
	global_load_dwordx4 v[88:91], v236, s[46:47] offset:448
	global_load_dwordx4 v[92:95], v236, s[48:49] offset:384
	global_load_dwordx4 v[96:99], v236, s[48:49] offset:448
	global_load_dwordx4 v[100:103], v236, s[50:51] offset:384
	global_load_dwordx4 v[104:107], v236, s[50:51] offset:448
	global_load_dwordx4 v[108:111], v236, s[52:53] offset:384
	global_load_dwordx4 v[112:115], v236, s[52:53] offset:448
	s_waitcnt vmcnt(24)
; #define GAS __attribute__((address_space(1)))
; __device__ __forceinline__ f32x4 mfma16(const bf16x8& a, const bf16x8& b, const f32x4& c) { return __builtin_amdgcn_mfma_f32_16x16x32_bf16(a, b, c, 0, 0, 0); }
; template <class F> __device__ __forceinline__ void skinny_tile_sk(const GAS bf16* A, int lda, const GAS bf16* Bt, int K, int n0, int wave, int lane, float* red, F&& epi) {
;     const int fr = lane & 15, fq = lane >> 4, kc = K >> 3;
;     const GAS bf16* ap = A + (size_t)fr * lda + wave * kc + fq * 8; const GAS bf16* bp = Bt + (size_t)(n0 + fr) * K + wave * kc + fq * 8;
;     f32x4 acc0 = {0.f, 0.f, 0.f, 0.f}, acc1 = {0.f, 0.f, 0.f, 0.f};
;     for (int k = 0; k < kc; k += 256) { bf16x8 a[8], bb[8];
; #pragma unroll
;         for (int i = 0; i < 8; ++i) { a[i] = *(const GAS bf16x8*)(ap + k + i * 32); bb[i] = *(const GAS bf16x8*)(bp + k + i * 32); }
; #pragma unroll
;         for (int i = 0; i < 8; i += 2) { acc0 = mfma16(a[i], bb[i], acc0); acc1 = mfma16(a[i + 1], bb[i + 1], acc1); } }
;     __syncthreads();
;     *(f32x4*)(red + wave * 256 + lane * 4) = acc0 + acc1;
;     __syncthreads();
;     if (wave == 0) { f32x4 s = {0.f, 0.f, 0.f, 0.f};
; #pragma unroll
;         for (int w = 0; w < 8; ++w) s += *(const f32x4*)(red + w * 256 + lane * 4);
	v_mfma_f32_16x16x32_bf16 v[36:39], v[120:123], v[136:139], v[36:39]
	v_mfma_f32_16x16x32_bf16 v[40:43], v[120:123], v[144:147], v[40:43]
	v_mfma_f32_16x16x32_bf16 v[44:47], v[120:123], v[152:155], v[44:47]
	v_mfma_f32_16x16x32_bf16 v[48:51], v[120:123], v[160:163], v[48:51]
	v_mfma_f32_16x16x32_bf16 v[52:55], v[128:131], v[136:139], v[52:55]
	v_mfma_f32_16x16x32_bf16 v[56:59], v[128:131], v[144:147], v[56:59]
	v_mfma_f32_16x16x32_bf16 v[60:63], v[128:131], v[152:155], v[60:63]
	v_mfma_f32_16x16x32_bf16 v[64:67], v[128:131], v[160:163], v[64:67]
	v_mfma_f32_16x16x32_bf16 v[36:39], v[124:127], v[140:143], v[36:39]
	v_mfma_f32_16x16x32_bf16 v[40:43], v[124:127], v[148:151], v[40:43]
	v_mfma_f32_16x16x32_bf16 v[44:47], v[124:127], v[156:159], v[44:47]
	v_mfma_f32_16x16x32_bf16 v[48:51], v[124:127], v[164:167], v[48:51]
	v_mfma_f32_16x16x32_bf16 v[52:55], v[132:135], v[140:143], v[52:55]
	v_mfma_f32_16x16x32_bf16 v[56:59], v[132:135], v[148:151], v[56:59]
	v_mfma_f32_16x16x32_bf16 v[60:63], v[132:135], v[156:159], v[60:63]
	v_mfma_f32_16x16x32_bf16 v[64:67], v[132:135], v[164:167], v[64:67]
	s_waitcnt vmcnt(12)
	v_mfma_f32_16x16x32_bf16 v[36:39], v[184:187], v[200:203], v[36:39]
	v_mfma_f32_16x16x32_bf16 v[40:43], v[184:187], v[208:211], v[40:43]
	v_mfma_f32_16x16x32_bf16 v[44:47], v[184:187], v[216:219], v[44:47]
	v_mfma_f32_16x16x32_bf16 v[48:51], v[184:187], v[224:227], v[48:51]
	v_mfma_f32_16x16x32_bf16 v[52:55], v[192:195], v[200:203], v[52:55]
	v_mfma_f32_16x16x32_bf16 v[56:59], v[192:195], v[208:211], v[56:59]
	v_mfma_f32_16x16x32_bf16 v[60:63], v[192:195], v[216:219], v[60:63]
	v_mfma_f32_16x16x32_bf16 v[64:67], v[192:195], v[224:227], v[64:67]
	v_mfma_f32_16x16x32_bf16 v[36:39], v[188:191], v[204:207], v[36:39]
	v_mfma_f32_16x16x32_bf16 v[40:43], v[188:191], v[212:215], v[40:43]
	v_mfma_f32_16x16x32_bf16 v[44:47], v[188:191], v[220:223], v[44:47]
	v_mfma_f32_16x16x32_bf16 v[48:51], v[188:191], v[228:231], v[48:51]
	v_mfma_f32_16x16x32_bf16 v[52:55], v[196:199], v[204:207], v[52:55]
	v_mfma_f32_16x16x32_bf16 v[56:59], v[196:199], v[212:215], v[56:59]
	v_mfma_f32_16x16x32_bf16 v[60:63], v[196:199], v[220:223], v[60:63]
	v_mfma_f32_16x16x32_bf16 v[64:67], v[196:199], v[228:231], v[64:67]
	s_waitcnt vmcnt(0)
	v_mfma_f32_16x16x32_bf16 v[36:39], v[68:71], v[84:87], v[36:39]
	v_mfma_f32_16x16x32_bf16 v[40:43], v[68:71], v[92:95], v[40:43]
	v_mfma_f32_16x16x32_bf16 v[44:47], v[68:71], v[100:103], v[44:47]
	v_mfma_f32_16x16x32_bf16 v[48:51], v[68:71], v[108:111], v[48:51]
	v_mfma_f32_16x16x32_bf16 v[52:55], v[76:79], v[84:87], v[52:55]
	v_mfma_f32_16x16x32_bf16 v[56:59], v[76:79], v[92:95], v[56:59]
	v_mfma_f32_16x16x32_bf16 v[60:63], v[76:79], v[100:103], v[60:63]
	v_mfma_f32_16x16x32_bf16 v[64:67], v[76:79], v[108:111], v[64:67]
	v_mfma_f32_16x16x32_bf16 v[36:39], v[72:75], v[88:91], v[36:39]
	v_mfma_f32_16x16x32_bf16 v[40:43], v[72:75], v[96:99], v[40:43]
	v_mfma_f32_16x16x32_bf16 v[44:47], v[72:75], v[104:107], v[44:47]
	v_mfma_f32_16x16x32_bf16 v[48:51], v[72:75], v[112:115], v[48:51]
	v_mfma_f32_16x16x32_bf16 v[52:55], v[80:83], v[88:91], v[52:55]
	v_mfma_f32_16x16x32_bf16 v[56:59], v[80:83], v[96:99], v[56:59]
	v_mfma_f32_16x16x32_bf16 v[60:63], v[80:83], v[104:107], v[60:63]
	v_mfma_f32_16x16x32_bf16 v[64:67], v[80:83], v[112:115], v[64:67]
	v_and_b32_e32 v18, 63, v172
	v_lshlrev_b32_e32 v18, 4, v18
	v_lshrrev_b32_e32 v19, 2, v116
	v_lshl_add_u32 v220, v116, 10, v18
	v_lshl_add_u32 v221, v19, 15, v220
	v_xor_b32_e32 v222, 1, v19
	v_lshl_add_u32 v222, v222, 15, v220
	s_nop 7
	ds_write_b128 v221, v[36:39] offset:0
	ds_write_b128 v222, v[52:55] offset:0
	ds_write_b128 v221, v[40:43] offset:8192
	ds_write_b128 v222, v[56:59] offset:8192
	ds_write_b128 v221, v[44:47] offset:16384
	ds_write_b128 v222, v[60:63] offset:16384
	ds_write_b128 v221, v[48:51] offset:24576
	ds_write_b128 v222, v[64:67] offset:24576
	s_waitcnt lgkmcnt(0)
	s_barrier
	v_lshl_add_u32 v19, v19, 2, v117
	v_lshl_add_u32 v19, v19, 13, v18
	ds_read_b128 v[68:71], v19 offset:0
	ds_read_b128 v[72:75], v19 offset:1024
	ds_read_b128 v[76:79], v19 offset:2048
	ds_read_b128 v[80:83], v19 offset:3072
	ds_read_b128 v[84:87], v19 offset:4096
	ds_read_b128 v[88:91], v19 offset:5120
	ds_read_b128 v[92:95], v19 offset:6144
	ds_read_b128 v[96:99], v19 offset:7168
	s_waitcnt lgkmcnt(0)
	v_add_f32_e32 v68, v68, v72
	v_add_f32_e32 v76, v76, v80
	v_add_f32_e32 v84, v84, v88
	v_add_f32_e32 v92, v92, v96
	v_add_f32_e32 v69, v69, v73
	v_add_f32_e32 v77, v77, v81
	v_add_f32_e32 v85, v85, v89
	v_add_f32_e32 v93, v93, v97
	v_add_f32_e32 v70, v70, v74
	v_add_f32_e32 v78, v78, v82
	v_add_f32_e32 v86, v86, v90
	v_add_f32_e32 v94, v94, v98
	v_add_f32_e32 v71, v71, v75
	v_add_f32_e32 v79, v79, v83
	v_add_f32_e32 v87, v87, v91
	v_add_f32_e32 v95, v95, v99
	v_add_f32_e32 v68, v68, v76
	v_add_f32_e32 v84, v84, v92
	v_add_f32_e32 v69, v69, v77
	v_add_f32_e32 v85, v85, v93
	v_add_f32_e32 v70, v70, v78
	v_add_f32_e32 v86, v86, v94
	v_add_f32_e32 v71, v71, v79
	v_add_f32_e32 v87, v87, v95
	v_add_f32_e32 v4, v68, v84
	v_add_f32_e32 v5, v69, v85
	v_add_f32_e32 v6, v70, v86
	v_add_f32_e32 v7, v71, v87
	v_mov_b32_e32 v8, 0
	v_mov_b32_e32 v9, 0
	v_mov_b32_e32 v10, 0
	v_mov_b32_e32 v11, 0
	v_or_b32_e32 v16, v16, v29
	v_lshlrev_b32_e32 v174, 2, v17
	v_ashrrev_i32_e32 v17, 31, v16
	v_lshl_add_u64 v[18:19], v[16:17], 2, s[14:15]
	s_mov_b32 s100, 0
	s_branch .Lsg1_join
